# v64 + nt on the remaining small P0 input loads and on the final f32 output stores (P10)
# speedup vs baseline: 1.0257x; 1.0034x over previous
.LBB0_17:
	s_andn2_b64 vcc, exec, s[0:1]
	s_cbranch_vccnz .LBB0_27
	s_add_i32 s0, s38, 0xfa80
	s_and_b32 s1, s0, 0xffff
	s_mul_i32 s1, s1, 0xba2f
	s_lshr_b32 s4, s1, 16
	s_lshr_b32 s1, s1, 22
	s_mulk_i32 s1, 0x58
	s_sub_i32 s0, s0, s1
	s_and_b32 s1, s0, 0xffff
	s_and_b32 s0, s4, 0xffc0
	v_or_b32_e32 v49, s0, v34
	s_lshl_b32 s6, s1, 7
	v_lshl_add_u64 v[2:3], v[44:45], 0, s[6:7]
	v_mul_u32_u24_e32 v36, 0x2c00, v49
	v_mad_u64_u32 v[4:5], s[4:5], v49, s29, v[2:3]
	v_lshl_add_u64 v[2:3], v[2:3], 0, v[36:37]
	v_add_co_u32_e32 v6, vcc, s30, v2
	v_cndmask_b32_e64 v36, 0, 1, s[8:9]
	s_nop 0
	v_addc_co_u32_e32 v7, vcc, 0, v3, vcc
	global_load_dwordx4 v[26:29], v[4:5], off nt
	global_load_dwordx4 v[30:33], v[6:7], off nt
	v_add_co_u32_e32 v4, vcc, s31, v2
	v_mov_b32_e32 v48, 1.0
	s_nop 0
	v_addc_co_u32_e32 v5, vcc, 0, v3, vcc
	v_add_co_u32_e32 v6, vcc, s36, v2
	v_cmp_ne_u32_e64 s[4:5], 1, v36
	s_nop 0
	v_addc_co_u32_e32 v7, vcc, 0, v3, vcc
	global_load_dwordx4 v[18:21], v[4:5], off nt
	global_load_dwordx4 v[22:25], v[6:7], off nt
	v_add_co_u32_e32 v4, vcc, s37, v2
	v_add_lshl_u32 v36, v34, s0, 2
	s_nop 0
	v_addc_co_u32_e32 v5, vcc, 0, v3, vcc
	v_add_co_u32_e32 v6, vcc, 0x6e000, v2
	v_mov_b32_e32 v60, 1.0
	s_nop 0
	v_addc_co_u32_e32 v7, vcc, 0, v3, vcc
	global_load_dwordx4 v[10:13], v[4:5], off nt
	global_load_dwordx4 v[14:17], v[6:7], off nt
	v_add_co_u32_e32 v4, vcc, 0x84000, v2
	s_nop 1
	v_addc_co_u32_e32 v5, vcc, 0, v3, vcc
	v_add_co_u32_e32 v6, vcc, 0x9a000, v2
	s_nop 1
	v_addc_co_u32_e32 v7, vcc, 0, v3, vcc
	global_load_dwordx4 v[2:5], v[4:5], off nt
	s_nop 0
	global_load_dwordx4 v[6:9], v[6:7], off nt
	s_andn2_b64 vcc, exec, s[8:9]
	s_cbranch_vccnz .LBB0_20
	v_lshlrev_b32_e32 v49, 2, v49
	global_load_dword v62, v49, s[72:73] nt
	global_load_dword v60, v36, s[72:73] offset:32 nt
	s_waitcnt vmcnt(1)
	v_pk_mul_f32 v[26:27], v[26:27], v[62:63] op_sel_hi:[1,0]
	v_pk_mul_f32 v[28:29], v[28:29], v[62:63] op_sel_hi:[1,0]
.LBB0_20:
	s_waitcnt vmcnt(0)
	v_mul_f32_e32 v30, v30, v60
	ds_write2_b32 v1, v26, v30 offset1:8
	v_mul_f32_e32 v26, v31, v60
	ds_write2_b32 v1, v27, v26 offset0:66 offset1:74
	v_mul_f32_e32 v26, v32, v60
	ds_write2_b32 v1, v28, v26 offset0:132 offset1:140
	v_mul_f32_e32 v26, v33, v60
	s_and_b64 vcc, exec, s[4:5]
	ds_write2_b32 v1, v29, v26 offset0:198 offset1:206
	s_cbranch_vccnz .LBB0_22
	global_load_dword v26, v36, s[72:73] offset:64 nt
	global_load_dword v48, v36, s[72:73] offset:96 nt
	s_waitcnt vmcnt(1)
	v_pk_mul_f32 v[18:19], v[18:19], v[26:27] op_sel_hi:[1,0]
	v_pk_mul_f32 v[20:21], v[20:21], v[26:27] op_sel_hi:[1,0]
.LBB0_22:
	s_waitcnt vmcnt(0)
	v_mul_f32_e32 v22, v22, v48
	ds_write2_b32 v1, v18, v22 offset0:16 offset1:24
	v_mul_f32_e32 v18, v23, v48
	ds_write2_b32 v1, v19, v18 offset0:82 offset1:90
	v_mul_f32_e32 v18, v24, v48
	ds_write2_b32 v1, v20, v18 offset0:148 offset1:156
	v_mul_f32_e32 v18, v25, v48
	ds_write2_b32 v1, v21, v18 offset0:214 offset1:222
	v_mov_b32_e32 v18, 1.0
	s_and_b64 vcc, exec, s[4:5]
	v_mov_b32_e32 v19, 1.0
	s_cbranch_vccnz .LBB0_24
	global_load_dword v20, v36, s[72:73] offset:128 nt
	global_load_dword v19, v36, s[72:73] offset:160 nt
	s_waitcnt vmcnt(1)
	v_pk_mul_f32 v[10:11], v[10:11], v[20:21] op_sel_hi:[1,0]
	v_pk_mul_f32 v[12:13], v[12:13], v[20:21] op_sel_hi:[1,0]
.LBB0_24:
	s_waitcnt vmcnt(0)
	v_mul_f32_e32 v14, v14, v19
	ds_write2_b32 v1, v10, v14 offset0:32 offset1:40
	v_mul_f32_e32 v10, v15, v19
	ds_write2_b32 v1, v11, v10 offset0:98 offset1:106
	v_mul_f32_e32 v10, v16, v19
	ds_write2_b32 v1, v12, v10 offset0:164 offset1:172
	v_mul_f32_e32 v10, v17, v19
	s_and_b64 vcc, exec, s[4:5]
	ds_write2_b32 v1, v13, v10 offset0:230 offset1:238
	s_cbranch_vccnz .LBB0_26
	global_load_dword v10, v36, s[72:73] offset:192 nt
	global_load_dword v18, v36, s[72:73] offset:224 nt
	s_waitcnt vmcnt(1)
	v_pk_mul_f32 v[2:3], v[2:3], v[10:11] op_sel_hi:[1,0]
	v_pk_mul_f32 v[4:5], v[4:5], v[10:11] op_sel_hi:[1,0]

.LBB0_28:
	s_andn2_b64 vcc, exec, s[0:1]
	s_cbranch_vccnz .LBB0_13
	s_mul_hi_i32 s0, s38, 0x2e8ba2e9
	s_lshr_b32 s1, s0, 31
	s_ashr_i32 s6, s0, 4
	s_add_i32 s6, s6, s1
	s_mul_i32 s0, s6, 0xfffff500
	s_lshl_b32 s4, s6, 6
	s_add_i32 s12, s14, s0
	v_or_b32_e32 v48, s4, v34
	s_ashr_i32 s13, s12, 31
	v_lshl_add_u64 v[2:3], s[12:13], 2, v[46:47]
	v_or_b32_e32 v6, 8, v48
	v_mad_i64_i32 v[4:5], s[0:1], v48, s29, v[2:3]
	v_mad_i64_i32 v[6:7], s[0:1], v6, s29, v[2:3]
	global_load_dwordx4 v[26:29], v[4:5], off nt
	global_load_dwordx4 v[30:33], v[6:7], off nt
	v_or_b32_e32 v4, 16, v48
	v_or_b32_e32 v6, 24, v48
	v_mad_i64_i32 v[4:5], s[0:1], v4, s29, v[2:3]
	v_mad_i64_i32 v[6:7], s[0:1], v6, s29, v[2:3]
	global_load_dwordx4 v[18:21], v[4:5], off nt
	global_load_dwordx4 v[22:25], v[6:7], off nt
	v_or_b32_e32 v4, 32, v48
	v_or_b32_e32 v6, 40, v48
	v_mad_i64_i32 v[4:5], s[0:1], v4, s29, v[2:3]
	v_mad_i64_i32 v[6:7], s[0:1], v6, s29, v[2:3]
	global_load_dwordx4 v[10:13], v[4:5], off nt
	global_load_dwordx4 v[14:17], v[6:7], off nt
	v_or_b32_e32 v4, 48, v48
	v_or_b32_e32 v6, 56, v48
	v_mad_i64_i32 v[4:5], s[0:1], v4, s29, v[2:3]
	v_mad_i64_i32 v[6:7], s[0:1], v6, s29, v[2:3]
	global_load_dwordx4 v[2:5], v[4:5], off nt
	s_nop 0
	global_load_dwordx4 v[6:9], v[6:7], off nt
	v_cndmask_b32_e64 v49, 0, 1, s[8:9]
	v_mov_b32_e32 v36, 1.0
	v_cmp_ne_u32_e64 s[0:1], 1, v49
	s_andn2_b64 vcc, exec, s[8:9]
	v_mov_b32_e32 v49, 1.0
	s_cbranch_vccnz .LBB0_31
	s_ashr_i32 s5, s4, 31
	v_ashrrev_i32_e32 v49, 31, v48
	v_lshl_add_u64 v[60:61], s[4:5], 0, v[34:35]
	v_lshl_add_u64 v[48:49], v[48:49], 2, s[72:73]
	v_lshl_add_u64 v[60:61], v[60:61], 2, s[72:73]
	global_load_dword v48, v[48:49], off nt
	s_nop 0
	global_load_dword v49, v[60:61], off offset:32 nt
	s_waitcnt vmcnt(0)
	v_pk_mul_f32 v[26:27], v[26:27], v[48:49] op_sel_hi:[1,0]
	v_pk_mul_f32 v[28:29], v[28:29], v[48:49] op_sel_hi:[1,0]
.LBB0_31:
	s_waitcnt vmcnt(6)
	v_mul_f32_e32 v30, v30, v49
	ds_write2_b32 v1, v26, v30 offset1:8
	v_mul_f32_e32 v26, v31, v49
	ds_write2_b32 v1, v27, v26 offset0:66 offset1:74
	v_mul_f32_e32 v26, v32, v49
	ds_write2_b32 v1, v28, v26 offset0:132 offset1:140
	v_mul_f32_e32 v26, v33, v49
	s_and_b64 vcc, exec, s[0:1]
	ds_write2_b32 v1, v29, v26 offset0:198 offset1:206
	s_cbranch_vccnz .LBB0_33
	s_ashr_i32 s5, s4, 31
	v_lshl_add_u64 v[26:27], s[4:5], 0, v[34:35]
	v_lshl_add_u64 v[26:27], v[26:27], 2, s[72:73]
	global_load_dword v28, v[26:27], off offset:64 nt
	global_load_dword v36, v[26:27], off offset:96 nt
	s_waitcnt vmcnt(1)
	v_pk_mul_f32 v[18:19], v[18:19], v[28:29] op_sel_hi:[1,0]
	v_pk_mul_f32 v[20:21], v[20:21], v[28:29] op_sel_hi:[1,0]
.LBB0_33:
	s_waitcnt vmcnt(0)
	v_mul_f32_e32 v22, v22, v36
	ds_write2_b32 v1, v18, v22 offset0:16 offset1:24
	v_mul_f32_e32 v18, v23, v36
	ds_write2_b32 v1, v19, v18 offset0:82 offset1:90
	v_mul_f32_e32 v18, v24, v36
	ds_write2_b32 v1, v20, v18 offset0:148 offset1:156
	v_mul_f32_e32 v18, v25, v36
	s_and_b64 vcc, exec, s[0:1]
	ds_write2_b32 v1, v21, v18 offset0:214 offset1:222
	s_cbranch_vccnz .LBB0_35
	s_ashr_i32 s5, s4, 31
	v_lshl_add_u64 v[18:19], s[4:5], 0, v[34:35]
	v_lshl_add_u64 v[18:19], v[18:19], 2, s[72:73]
	global_load_dword v20, v[18:19], off offset:128 nt
	s_nop 0
	global_load_dword v18, v[18:19], off offset:160 nt
	s_waitcnt vmcnt(1)
	v_pk_mul_f32 v[10:11], v[10:11], v[20:21] op_sel_hi:[1,0]
	v_pk_mul_f32 v[12:13], v[12:13], v[20:21] op_sel_hi:[1,0]
	s_branch .LBB0_36

.LBB0_36:
	s_waitcnt vmcnt(0)
	v_mul_f32_e32 v14, v14, v18
	ds_write2_b32 v1, v10, v14 offset0:32 offset1:40
	v_mul_f32_e32 v10, v15, v18
	ds_write2_b32 v1, v11, v10 offset0:98 offset1:106
	v_mul_f32_e32 v10, v16, v18
	ds_write2_b32 v1, v12, v10 offset0:164 offset1:172
	v_mul_f32_e32 v10, v17, v18
	s_and_b64 vcc, exec, s[8:9]
	ds_write2_b32 v1, v13, v10 offset0:230 offset1:238
	s_cbranch_vccz .LBB0_38
	s_ashr_i32 s5, s4, 31
	v_lshl_add_u64 v[10:11], s[4:5], 0, v[34:35]
	v_lshl_add_u64 v[10:11], v[10:11], 2, s[72:73]
	global_load_dword v12, v[10:11], off offset:192 nt
	s_nop 0
	global_load_dword v10, v[10:11], off offset:224 nt
	s_waitcnt vmcnt(1)
	v_pk_mul_f32 v[2:3], v[2:3], v[12:13] op_sel_hi:[1,0]
	v_pk_mul_f32 v[4:5], v[4:5], v[12:13] op_sel_hi:[1,0]
	s_cbranch_execnz .LBB0_12
	s_branch .LBB0_39

.LBB0_64:
	s_movk_i32 s4, 0x1800
	v_cmp_gt_u32_e32 vcc, s4, v1
	s_and_saveexec_b64 s[4:5], vcc
	s_cbranch_execz .LBB0_66
	v_readlane_b32 s8, v253, 18
	s_movk_i32 s6, 0x1600
	v_readlane_b32 s9, v253, 19
	v_readlane_b32 s11, v253, 21
	v_readlane_b32 s10, v253, 20
	v_mov_b32_e32 v3, s9
	v_mov_b32_e32 v2, s11
	v_cmp_gt_u32_e32 vcc, s6, v1
	v_mov_b32_e32 v1, s10
	s_waitcnt lgkmcnt(0)
	v_lshlrev_b32_e32 v4, 2, v0
	v_cndmask_b32_e32 v3, v2, v3, vcc
	v_mov_b32_e32 v2, s8
	v_mov_b32_e32 v5, 0
	v_cndmask_b32_e32 v2, v1, v2, vcc
	v_or_b32_e32 v8, 0x800, v4
	v_mov_b32_e32 v9, v5
	v_lshl_add_u64 v[6:7], v[2:3], 0, v[4:5]
	v_lshl_add_u64 v[2:3], v[2:3], 0, v[8:9]
	global_load_dword v1, v[6:7], off nt
	s_nop 0
	global_load_dword v2, v[2:3], off nt
	v_mov_b32_e32 v6, 0x10a800
	v_mov_b32_e32 v3, v5
	v_readlane_b32 s12, v253, 22
	v_readlane_b32 s13, v253, 23
	v_readlane_b32 s14, v253, 24
	v_readlane_b32 s15, v253, 25
	v_readlane_b32 s16, v253, 26
	v_readlane_b32 s17, v253, 27
	v_readlane_b32 s18, v253, 28
	v_readlane_b32 s19, v253, 29
	v_readlane_b32 s20, v253, 30
	v_readlane_b32 s21, v253, 31
	v_readlane_b32 s22, v253, 32
	v_readlane_b32 s23, v253, 33
	s_waitcnt vmcnt(0)
	v_sub_f32_e32 v1, v1, v2
	v_mul_f32_e32 v1, 0x3fb8aa3b, v1
	v_exp_f32_e32 v1, v1
	v_mov_b32_e32 v2, 0x10a000
	v_cndmask_b32_e32 v2, v6, v2, vcc
	v_lshl_add_u64 v[2:3], s[86:87], 0, v[2:3]
	v_add_f32_e32 v1, 1.0, v1
	v_div_scale_f32 v6, s[6:7], v1, v1, 1.0
	v_rcp_f32_e32 v7, v6
	v_div_scale_f32 v8, vcc, 1.0, v1, 1.0
	v_lshl_add_u64 v[2:3], v[2:3], 0, v[4:5]
	v_fma_f32 v9, -v6, v7, 1.0
	v_fmac_f32_e32 v7, v9, v7
	v_mul_f32_e32 v9, v8, v7
	v_fma_f32 v10, -v6, v9, v8
	v_fmac_f32_e32 v9, v10, v7
	v_fma_f32 v6, -v6, v9, v8
	v_div_fmas_f32 v6, v6, v7, v9
	v_div_fixup_f32 v1, v6, v1, 1.0
	global_store_dword v[2:3], v1, off

.LBB0_2073:
	s_andn2_b32 s33, s33, 63
	v_and_or_b32 v130, v1, 32, s33
	v_ashrrev_i32_e32 v163, 5, v130
	v_lshl_add_u32 v164, s39, 8, v163
	v_ashrrev_i32_e32 v165, 31, v164
	s_lshl_b32 s0, s38, 8
	v_lshlrev_b32_e32 v1, 3, v1
	v_lshlrev_b64 v[130:131], 11, v[164:165]
	s_ashr_i32 s1, s0, 31
	v_and_b32_e32 v1, 0xf8, v1
	v_lshl_add_u64 v[130:131], s[88:89], 0, v[130:131]
	s_lshl_b64 s[4:5], s[0:1], 1
	v_lshl_add_u64 v[130:131], v[130:131], 0, s[4:5]
	v_lshlrev_b32_e32 v166, 1, v1
	v_mov_b32_e32 v167, 0
	v_lshl_add_u64 v[130:131], v[130:131], 0, v[166:167]
	s_mov_b32 s6, 0x8000
	v_add_co_u32_e32 v132, vcc, s6, v130
	s_mov_b32 s7, 0x10000
	s_nop 0
	v_addc_co_u32_e32 v133, vcc, 0, v131, vcc
	s_waitcnt vmcnt(0)
	s_barrier
	global_load_dwordx4 v[158:161], v[130:131], off
	global_load_dwordx4 v[154:157], v[132:133], off
	v_add_co_u32_e32 v132, vcc, s7, v130
	s_mov_b32 s8, 0x18000
	s_nop 0
	v_addc_co_u32_e32 v133, vcc, 0, v131, vcc
	v_add_co_u32_e32 v134, vcc, s8, v130
	s_mov_b32 s9, 0x20000
	s_nop 0
	v_addc_co_u32_e32 v135, vcc, 0, v131, vcc
	global_load_dwordx4 v[150:153], v[132:133], off
	global_load_dwordx4 v[146:149], v[134:135], off
	v_add_co_u32_e32 v132, vcc, s9, v130
	s_mov_b32 s10, 0x28000
	s_nop 0
	v_addc_co_u32_e32 v133, vcc, 0, v131, vcc
	v_add_co_u32_e32 v134, vcc, s10, v130
	s_mov_b32 s11, 0x30000
	s_nop 0
	v_addc_co_u32_e32 v135, vcc, 0, v131, vcc
	global_load_dwordx4 v[142:145], v[132:133], off
	global_load_dwordx4 v[138:141], v[134:135], off
	v_add_co_u32_e32 v132, vcc, s11, v130
	s_mov_b32 s12, 0x38000
	s_nop 0
	v_addc_co_u32_e32 v133, vcc, 0, v131, vcc
	v_add_co_u32_e32 v130, vcc, s12, v130
	s_lshl_b32 s12, s40, 7
	s_add_i32 s12, s12, 0
	v_add_u32_e32 v162, s12, v215
	s_movk_i32 s12, 0x410
	v_mul_lo_u32 v168, v214, s12
	v_addc_co_u32_e32 v131, vcc, 0, v131, vcc
	v_add_u32_e32 v162, v162, v168
	global_load_dwordx4 v[134:137], v[132:133], off
	s_nop 0
	global_load_dwordx4 v[130:133], v[130:131], off
	ds_write_b128 v162, v[66:69]
	ds_write_b128 v162, v[70:73] offset:64
	ds_write_b128 v162, v[74:77] offset:16640
	ds_write_b128 v162, v[78:81] offset:16704
	ds_write_b128 v162, v[82:85] offset:33280
	ds_write_b128 v162, v[86:89] offset:33344
	ds_write_b128 v162, v[90:93] offset:49920
	ds_write_b128 v162, v[94:97] offset:49984
	ds_write_b128 v162, v[98:101] offset:512
	ds_write_b128 v162, v[102:105] offset:576
	ds_write_b128 v162, v[106:109] offset:17152
	ds_write_b128 v162, v[110:113] offset:17216
	ds_write_b128 v162, v[114:117] offset:33792
	ds_write_b128 v162, v[118:121] offset:33856
	ds_write_b128 v162, v[122:125] offset:50432
	ds_write_b128 v162, v[126:129] offset:50496
	v_add_u32_e32 v98, 0x80, v164
	v_ashrrev_i32_e32 v99, 31, v98
	v_lshlrev_b64 v[66:67], 11, v[98:99]
	v_lshl_add_u64 v[66:67], s[88:89], 0, v[66:67]
	v_lshl_add_u64 v[66:67], v[66:67], 0, s[4:5]
	v_lshl_add_u64 v[66:67], v[66:67], 0, v[166:167]
	v_add_co_u32_e32 v68, vcc, s6, v66
	s_waitcnt vmcnt(0) lgkmcnt(0)
	s_nop 0
	v_addc_co_u32_e32 v69, vcc, 0, v67, vcc
	s_barrier
	global_load_dwordx4 v[94:97], v[66:67], off
	global_load_dwordx4 v[90:93], v[68:69], off
	v_add_co_u32_e32 v68, vcc, s7, v66
	v_or_b32_e32 v100, s0, v1
	s_nop 0
	v_addc_co_u32_e32 v69, vcc, 0, v67, vcc
	v_add_co_u32_e32 v70, vcc, s8, v66
	v_mov_b32_e32 v101, s1
	s_nop 0
	v_addc_co_u32_e32 v71, vcc, 0, v67, vcc
	global_load_dwordx4 v[86:89], v[68:69], off
	global_load_dwordx4 v[82:85], v[70:71], off
	v_add_co_u32_e32 v68, vcc, s9, v66
	v_lshlrev_b64 v[102:103], 10, v[164:165]
	s_nop 0
	v_addc_co_u32_e32 v69, vcc, 0, v67, vcc
	v_add_co_u32_e32 v70, vcc, s10, v66
	v_lshlrev_b32_e32 v104, 2, v1
	s_nop 0
	v_addc_co_u32_e32 v71, vcc, 0, v67, vcc
	global_load_dwordx4 v[78:81], v[68:69], off
	global_load_dwordx4 v[74:77], v[70:71], off
	v_add_co_u32_e32 v68, vcc, s11, v66
	v_lshl_add_u64 v[102:103], v[102:103], 0, v[100:101]
	s_nop 0
	v_addc_co_u32_e32 v69, vcc, 0, v67, vcc
	v_add_co_u32_e32 v66, vcc, 0x38000, v66
	v_mul_lo_u32 v1, v163, s12
	s_nop 0
	v_addc_co_u32_e32 v67, vcc, 0, v67, vcc
	global_load_dwordx4 v[70:73], v[68:69], off
	s_nop 0
	global_load_dwordx4 v[66:69], v[66:67], off
	s_cmp_lg_u64 s[84:85], 0
	v_add3_u32 v1, 0, v104, v1
	s_cselect_b64 s[4:5], -1, 0
	s_cmp_eq_u64 s[84:85], 0
	v_lshl_add_u64 v[102:103], v[102:103], 2, s[84:85]
	s_cbranch_scc1 .LBB0_2075
	ds_read_b128 v[104:107], v1
	ds_read_b128 v[108:111], v1 offset:16
	v_lshlrev_b32_e32 v112, 16, v160
	v_and_b32_e32 v113, 0xffff0000, v160
	v_lshlrev_b32_e32 v114, 16, v161
	v_and_b32_e32 v115, 0xffff0000, v161
	s_waitcnt lgkmcnt(0)
	v_pk_fma_f32 v[110:111], v[110:111], 0.5, v[114:115] op_sel_hi:[1,0,1]
	v_pk_fma_f32 v[108:109], v[108:109], 0.5, v[112:113] op_sel_hi:[1,0,1]
	v_lshlrev_b32_e32 v112, 16, v158
	v_and_b32_e32 v113, 0xffff0000, v158
	v_lshlrev_b32_e32 v114, 16, v159
	v_and_b32_e32 v115, 0xffff0000, v159
	v_pk_fma_f32 v[106:107], v[106:107], 0.5, v[114:115] op_sel_hi:[1,0,1]
	v_pk_fma_f32 v[104:105], v[104:105], 0.5, v[112:113] op_sel_hi:[1,0,1]
	global_store_dwordx4 v[102:103], v[104:107], off nt
	global_store_dwordx4 v[102:103], v[108:111], off offset:16 nt
.LBB0_2075:
	s_nop 0
	v_cndmask_b32_e64 v104, 0, 1, s[4:5]
	v_cmp_ne_u32_e64 s[0:1], 1, v104
	s_andn2_b64 vcc, exec, s[4:5]
	s_cbranch_vccnz .LBB0_2077
	ds_read_b128 v[104:107], v1 offset:16640
	ds_read_b128 v[108:111], v1 offset:16656
	v_lshlrev_b32_e32 v112, 16, v156
	v_and_b32_e32 v113, 0xffff0000, v156
	v_lshlrev_b32_e32 v114, 16, v157
	v_and_b32_e32 v115, 0xffff0000, v157
	s_waitcnt lgkmcnt(0)
	v_pk_fma_f32 v[108:109], v[108:109], 0.5, v[112:113] op_sel_hi:[1,0,1]
	v_lshlrev_b32_e32 v112, 16, v154
	v_and_b32_e32 v113, 0xffff0000, v154
	v_pk_fma_f32 v[110:111], v[110:111], 0.5, v[114:115] op_sel_hi:[1,0,1]
	v_lshlrev_b32_e32 v114, 16, v155
	v_and_b32_e32 v115, 0xffff0000, v155
	v_pk_fma_f32 v[104:105], v[104:105], 0.5, v[112:113] op_sel_hi:[1,0,1]
	v_add_co_u32_e32 v112, vcc, 0x10000, v102
	v_pk_fma_f32 v[106:107], v[106:107], 0.5, v[114:115] op_sel_hi:[1,0,1]
	s_nop 0
	v_addc_co_u32_e32 v113, vcc, 0, v103, vcc
	global_store_dwordx4 v[112:113], v[104:107], off nt
	global_store_dwordx4 v[112:113], v[108:111], off offset:16 nt
.LBB0_2077:
	s_and_b64 vcc, exec, s[0:1]
	s_cbranch_vccnz .LBB0_2079
	ds_read_b128 v[104:107], v1 offset:33280
	ds_read_b128 v[108:111], v1 offset:33296
	v_lshlrev_b32_e32 v112, 16, v152
	v_and_b32_e32 v113, 0xffff0000, v152
	v_lshlrev_b32_e32 v114, 16, v153
	v_and_b32_e32 v115, 0xffff0000, v153
	s_waitcnt lgkmcnt(0)
	v_pk_fma_f32 v[108:109], v[108:109], 0.5, v[112:113] op_sel_hi:[1,0,1]
	v_lshlrev_b32_e32 v112, 16, v150
	v_and_b32_e32 v113, 0xffff0000, v150
	v_pk_fma_f32 v[110:111], v[110:111], 0.5, v[114:115] op_sel_hi:[1,0,1]
	v_lshlrev_b32_e32 v114, 16, v151
	v_and_b32_e32 v115, 0xffff0000, v151
	v_pk_fma_f32 v[104:105], v[104:105], 0.5, v[112:113] op_sel_hi:[1,0,1]
	v_add_co_u32_e32 v112, vcc, 0x20000, v102
	v_pk_fma_f32 v[106:107], v[106:107], 0.5, v[114:115] op_sel_hi:[1,0,1]
	s_nop 0
	v_addc_co_u32_e32 v113, vcc, 0, v103, vcc
	global_store_dwordx4 v[112:113], v[104:107], off nt
	global_store_dwordx4 v[112:113], v[108:111], off offset:16 nt
.LBB0_2079:
	s_and_b64 vcc, exec, s[0:1]
	s_cbranch_vccnz .LBB0_2081
	ds_read_b128 v[104:107], v1 offset:49920
	ds_read_b128 v[108:111], v1 offset:49936
	v_lshlrev_b32_e32 v112, 16, v148
	v_and_b32_e32 v113, 0xffff0000, v148
	v_lshlrev_b32_e32 v114, 16, v149
	v_and_b32_e32 v115, 0xffff0000, v149
	s_waitcnt lgkmcnt(0)
	v_pk_fma_f32 v[108:109], v[108:109], 0.5, v[112:113] op_sel_hi:[1,0,1]
	v_lshlrev_b32_e32 v112, 16, v146
	v_and_b32_e32 v113, 0xffff0000, v146
	v_pk_fma_f32 v[110:111], v[110:111], 0.5, v[114:115] op_sel_hi:[1,0,1]
	v_lshlrev_b32_e32 v114, 16, v147
	v_and_b32_e32 v115, 0xffff0000, v147
	v_pk_fma_f32 v[104:105], v[104:105], 0.5, v[112:113] op_sel_hi:[1,0,1]
	v_add_co_u32_e32 v112, vcc, 0x30000, v102
	v_pk_fma_f32 v[106:107], v[106:107], 0.5, v[114:115] op_sel_hi:[1,0,1]
	s_nop 0
	v_addc_co_u32_e32 v113, vcc, 0, v103, vcc
	global_store_dwordx4 v[112:113], v[104:107], off nt
	global_store_dwordx4 v[112:113], v[108:111], off offset:16 nt
.LBB0_2081:
	s_nop 0
	v_add_u32_e32 v104, 0x10400, v1
	s_and_b64 vcc, exec, s[0:1]
	v_add_u32_e32 v106, 0x10410, v1
	s_cbranch_vccnz .LBB0_2083
	ds_read_b128 v[108:111], v106
	ds_read_b128 v[112:115], v104
	v_lshlrev_b32_e32 v116, 16, v144
	v_and_b32_e32 v117, 0xffff0000, v144
	v_lshlrev_b32_e32 v118, 16, v145
	v_and_b32_e32 v119, 0xffff0000, v145
	s_waitcnt lgkmcnt(1)
	v_pk_fma_f32 v[108:109], v[108:109], 0.5, v[116:117] op_sel_hi:[1,0,1]
	v_lshlrev_b32_e32 v116, 16, v142
	v_and_b32_e32 v117, 0xffff0000, v142
	v_pk_fma_f32 v[110:111], v[110:111], 0.5, v[118:119] op_sel_hi:[1,0,1]
	v_lshlrev_b32_e32 v118, 16, v143
	v_and_b32_e32 v119, 0xffff0000, v143
	s_waitcnt lgkmcnt(0)
	v_pk_fma_f32 v[112:113], v[112:113], 0.5, v[116:117] op_sel_hi:[1,0,1]
	v_add_co_u32_e32 v116, vcc, 0x40000, v102
	v_pk_fma_f32 v[114:115], v[114:115], 0.5, v[118:119] op_sel_hi:[1,0,1]
	s_nop 0
	v_addc_co_u32_e32 v117, vcc, 0, v103, vcc
	global_store_dwordx4 v[116:117], v[112:115], off nt
	global_store_dwordx4 v[116:117], v[108:111], off offset:16 nt
.LBB0_2083:
	v_add_u32_e32 v105, 0x14500, v1
	s_and_b64 vcc, exec, s[0:1]
	v_add_u32_e32 v108, 0x14510, v1
	s_cbranch_vccnz .LBB0_2085
	ds_read_b128 v[110:113], v108
	ds_read_b128 v[114:117], v105
	v_lshlrev_b32_e32 v118, 16, v140
	v_and_b32_e32 v119, 0xffff0000, v140
	v_lshlrev_b32_e32 v120, 16, v141
	v_and_b32_e32 v121, 0xffff0000, v141
	s_waitcnt lgkmcnt(1)
	v_pk_fma_f32 v[110:111], v[110:111], 0.5, v[118:119] op_sel_hi:[1,0,1]
	v_lshlrev_b32_e32 v118, 16, v138
	v_and_b32_e32 v119, 0xffff0000, v138
	v_pk_fma_f32 v[112:113], v[112:113], 0.5, v[120:121] op_sel_hi:[1,0,1]
	v_lshlrev_b32_e32 v120, 16, v139
	v_and_b32_e32 v121, 0xffff0000, v139
	s_waitcnt lgkmcnt(0)
	v_pk_fma_f32 v[114:115], v[114:115], 0.5, v[118:119] op_sel_hi:[1,0,1]
	v_add_co_u32_e32 v118, vcc, 0x50000, v102
	v_pk_fma_f32 v[116:117], v[116:117], 0.5, v[120:121] op_sel_hi:[1,0,1]
	s_nop 0
	v_addc_co_u32_e32 v119, vcc, 0, v103, vcc
	global_store_dwordx4 v[118:119], v[114:117], off nt
	global_store_dwordx4 v[118:119], v[110:113], off offset:16 nt
.LBB0_2085:
	v_add_u32_e32 v107, 0x18600, v1
	s_and_b64 vcc, exec, s[0:1]
	v_add_u32_e32 v110, 0x18610, v1
	s_cbranch_vccnz .LBB0_2087
	ds_read_b128 v[112:115], v110
	ds_read_b128 v[116:119], v107
	v_lshlrev_b32_e32 v120, 16, v136
	v_and_b32_e32 v121, 0xffff0000, v136
	v_lshlrev_b32_e32 v122, 16, v137
	v_and_b32_e32 v123, 0xffff0000, v137
	s_waitcnt lgkmcnt(1)
	v_pk_fma_f32 v[112:113], v[112:113], 0.5, v[120:121] op_sel_hi:[1,0,1]
	v_lshlrev_b32_e32 v120, 16, v134
	v_and_b32_e32 v121, 0xffff0000, v134
	v_pk_fma_f32 v[114:115], v[114:115], 0.5, v[122:123] op_sel_hi:[1,0,1]
	v_lshlrev_b32_e32 v122, 16, v135
	v_and_b32_e32 v123, 0xffff0000, v135
	s_waitcnt lgkmcnt(0)
	v_pk_fma_f32 v[116:117], v[116:117], 0.5, v[120:121] op_sel_hi:[1,0,1]
	v_add_co_u32_e32 v120, vcc, 0x60000, v102
	v_pk_fma_f32 v[118:119], v[118:119], 0.5, v[122:123] op_sel_hi:[1,0,1]
	s_nop 0
	v_addc_co_u32_e32 v121, vcc, 0, v103, vcc
	global_store_dwordx4 v[120:121], v[116:119], off nt
	global_store_dwordx4 v[120:121], v[112:115], off offset:16 nt
.LBB0_2087:
	v_add_u32_e32 v109, 0x1c700, v1
	s_and_b64 vcc, exec, s[0:1]
	v_add_u32_e32 v111, 0x1c710, v1
	s_cbranch_vccnz .LBB0_2089
	ds_read_b128 v[112:115], v111
	ds_read_b128 v[116:119], v109
	v_lshlrev_b32_e32 v120, 16, v132
	v_and_b32_e32 v121, 0xffff0000, v132
	v_lshlrev_b32_e32 v122, 16, v133
	v_and_b32_e32 v123, 0xffff0000, v133
	s_waitcnt lgkmcnt(1)
	v_pk_fma_f32 v[114:115], v[114:115], 0.5, v[122:123] op_sel_hi:[1,0,1]
	v_pk_fma_f32 v[112:113], v[112:113], 0.5, v[120:121] op_sel_hi:[1,0,1]
	v_lshlrev_b32_e32 v120, 16, v130
	v_and_b32_e32 v121, 0xffff0000, v130
	v_lshlrev_b32_e32 v122, 16, v131
	v_and_b32_e32 v123, 0xffff0000, v131
	v_add_co_u32_e32 v102, vcc, 0x70000, v102
	s_waitcnt lgkmcnt(0)
	v_pk_fma_f32 v[118:119], v[118:119], 0.5, v[122:123] op_sel_hi:[1,0,1]
	v_pk_fma_f32 v[116:117], v[116:117], 0.5, v[120:121] op_sel_hi:[1,0,1]
	v_addc_co_u32_e32 v103, vcc, 0, v103, vcc
	global_store_dwordx4 v[102:103], v[116:119], off nt
	global_store_dwordx4 v[102:103], v[112:115], off offset:16 nt
.LBB0_2089:
	s_and_b64 vcc, exec, s[0:1]
	s_barrier
	ds_write_b128 v162, v[2:5]
	ds_write_b128 v162, v[6:9] offset:64
	ds_write_b128 v162, v[10:13] offset:16640
	ds_write_b128 v162, v[14:17] offset:16704
	ds_write_b128 v162, v[18:21] offset:33280
	ds_write_b128 v162, v[22:25] offset:33344
	ds_write_b128 v162, v[26:29] offset:49920
	ds_write_b128 v162, v[30:33] offset:49984
	ds_write_b128 v162, v[34:37] offset:512
	ds_write_b128 v162, v[38:41] offset:576
	ds_write_b128 v162, v[42:45] offset:17152
	ds_write_b128 v162, v[46:49] offset:17216
	ds_write_b128 v162, v[50:53] offset:33792
	ds_write_b128 v162, v[54:57] offset:33856
	ds_write_b128 v162, v[58:61] offset:50432
	ds_write_b128 v162, v[62:65] offset:50496
	s_waitcnt lgkmcnt(0)
	s_barrier
	s_cbranch_vccnz .LBB0_2091
	ds_read_b128 v[4:7], v1
	ds_read_b128 v[8:11], v1 offset:16
	v_lshlrev_b64 v[2:3], 12, v[98:99]
	s_waitcnt vmcnt(7)
	v_lshlrev_b32_e32 v12, 16, v96
	v_and_b32_e32 v13, 0xffff0000, v96
	v_lshlrev_b32_e32 v14, 16, v97
	v_and_b32_e32 v15, 0xffff0000, v97
	v_lshl_add_u64 v[2:3], s[84:85], 0, v[2:3]
	s_waitcnt lgkmcnt(0)
	v_pk_fma_f32 v[10:11], v[10:11], 0.5, v[14:15] op_sel_hi:[1,0,1]
	v_pk_fma_f32 v[8:9], v[8:9], 0.5, v[12:13] op_sel_hi:[1,0,1]
	v_lshlrev_b32_e32 v12, 16, v94
	v_and_b32_e32 v13, 0xffff0000, v94
	v_lshlrev_b32_e32 v14, 16, v95
	v_and_b32_e32 v15, 0xffff0000, v95
	v_lshl_add_u64 v[2:3], v[100:101], 2, v[2:3]
	v_pk_fma_f32 v[6:7], v[6:7], 0.5, v[14:15] op_sel_hi:[1,0,1]
	v_pk_fma_f32 v[4:5], v[4:5], 0.5, v[12:13] op_sel_hi:[1,0,1]
	global_store_dwordx4 v[2:3], v[4:7], off nt
	global_store_dwordx4 v[2:3], v[8:11], off offset:16 nt
	ds_read_b128 v[4:7], v1 offset:16656
	ds_read_b128 v[8:11], v1 offset:16640
	s_waitcnt vmcnt(8)
	v_lshlrev_b32_e32 v12, 16, v92
	v_and_b32_e32 v13, 0xffff0000, v92
	v_lshlrev_b32_e32 v14, 16, v93
	v_and_b32_e32 v15, 0xffff0000, v93
	s_waitcnt lgkmcnt(1)
	v_pk_fma_f32 v[4:5], v[4:5], 0.5, v[12:13] op_sel_hi:[1,0,1]
	v_lshlrev_b32_e32 v12, 16, v90
	v_and_b32_e32 v13, 0xffff0000, v90
	s_mov_b32 s0, 0x10000
	v_pk_fma_f32 v[6:7], v[6:7], 0.5, v[14:15] op_sel_hi:[1,0,1]
	v_lshlrev_b32_e32 v14, 16, v91
	v_and_b32_e32 v15, 0xffff0000, v91
	s_waitcnt lgkmcnt(0)
	v_pk_fma_f32 v[8:9], v[8:9], 0.5, v[12:13] op_sel_hi:[1,0,1]
	v_add_co_u32_e32 v12, vcc, s0, v2
	v_pk_fma_f32 v[10:11], v[10:11], 0.5, v[14:15] op_sel_hi:[1,0,1]
	s_nop 0
	v_addc_co_u32_e32 v13, vcc, 0, v3, vcc
	global_store_dwordx4 v[12:13], v[8:11], off nt
	global_store_dwordx4 v[12:13], v[4:7], off offset:16 nt
	ds_read_b128 v[4:7], v1 offset:33296
	ds_read_b128 v[8:11], v1 offset:33280
	s_waitcnt vmcnt(9)
	v_lshlrev_b32_e32 v12, 16, v88
	v_and_b32_e32 v13, 0xffff0000, v88
	v_lshlrev_b32_e32 v14, 16, v89
	v_and_b32_e32 v15, 0xffff0000, v89
	s_waitcnt lgkmcnt(1)
	v_pk_fma_f32 v[4:5], v[4:5], 0.5, v[12:13] op_sel_hi:[1,0,1]
	v_lshlrev_b32_e32 v12, 16, v86
	v_and_b32_e32 v13, 0xffff0000, v86
	s_mov_b32 s0, 0x20000
	v_pk_fma_f32 v[6:7], v[6:7], 0.5, v[14:15] op_sel_hi:[1,0,1]
	v_lshlrev_b32_e32 v14, 16, v87
	v_and_b32_e32 v15, 0xffff0000, v87
	s_waitcnt lgkmcnt(0)
	v_pk_fma_f32 v[8:9], v[8:9], 0.5, v[12:13] op_sel_hi:[1,0,1]
	v_add_co_u32_e32 v12, vcc, s0, v2
	v_pk_fma_f32 v[10:11], v[10:11], 0.5, v[14:15] op_sel_hi:[1,0,1]
	s_nop 0
	v_addc_co_u32_e32 v13, vcc, 0, v3, vcc
	global_store_dwordx4 v[12:13], v[8:11], off nt
	global_store_dwordx4 v[12:13], v[4:7], off offset:16 nt
	ds_read_b128 v[4:7], v1 offset:49936
	ds_read_b128 v[8:11], v1 offset:49920
	s_waitcnt vmcnt(10)
	v_lshlrev_b32_e32 v12, 16, v84
	v_and_b32_e32 v13, 0xffff0000, v84
	v_lshlrev_b32_e32 v14, 16, v85
	v_and_b32_e32 v15, 0xffff0000, v85
	s_waitcnt lgkmcnt(1)
	v_pk_fma_f32 v[4:5], v[4:5], 0.5, v[12:13] op_sel_hi:[1,0,1]
	v_lshlrev_b32_e32 v12, 16, v82
	v_and_b32_e32 v13, 0xffff0000, v82
	s_mov_b32 s0, 0x30000
	v_pk_fma_f32 v[6:7], v[6:7], 0.5, v[14:15] op_sel_hi:[1,0,1]
	v_lshlrev_b32_e32 v14, 16, v83
	v_and_b32_e32 v15, 0xffff0000, v83
	s_waitcnt lgkmcnt(0)
	v_pk_fma_f32 v[8:9], v[8:9], 0.5, v[12:13] op_sel_hi:[1,0,1]
	v_add_co_u32_e32 v12, vcc, s0, v2
	v_pk_fma_f32 v[10:11], v[10:11], 0.5, v[14:15] op_sel_hi:[1,0,1]
	s_nop 0
	v_addc_co_u32_e32 v13, vcc, 0, v3, vcc
	global_store_dwordx4 v[12:13], v[8:11], off nt
	global_store_dwordx4 v[12:13], v[4:7], off offset:16 nt
	ds_read_b128 v[4:7], v106
	ds_read_b128 v[8:11], v104
	s_waitcnt vmcnt(11)
	v_lshlrev_b32_e32 v12, 16, v80
	v_and_b32_e32 v13, 0xffff0000, v80
	v_lshlrev_b32_e32 v14, 16, v81
	v_and_b32_e32 v15, 0xffff0000, v81
	s_waitcnt lgkmcnt(1)
	v_pk_fma_f32 v[4:5], v[4:5], 0.5, v[12:13] op_sel_hi:[1,0,1]
	v_lshlrev_b32_e32 v12, 16, v78
	v_and_b32_e32 v13, 0xffff0000, v78
	s_mov_b32 s0, 0x40000
	v_pk_fma_f32 v[6:7], v[6:7], 0.5, v[14:15] op_sel_hi:[1,0,1]
	v_lshlrev_b32_e32 v14, 16, v79
	v_and_b32_e32 v15, 0xffff0000, v79
	s_waitcnt lgkmcnt(0)
	v_pk_fma_f32 v[8:9], v[8:9], 0.5, v[12:13] op_sel_hi:[1,0,1]
	v_add_co_u32_e32 v12, vcc, s0, v2
	v_pk_fma_f32 v[10:11], v[10:11], 0.5, v[14:15] op_sel_hi:[1,0,1]
	s_nop 0
	v_addc_co_u32_e32 v13, vcc, 0, v3, vcc
	global_store_dwordx4 v[12:13], v[8:11], off nt
	global_store_dwordx4 v[12:13], v[4:7], off offset:16 nt
	ds_read_b128 v[4:7], v108
	ds_read_b128 v[8:11], v105
	s_waitcnt vmcnt(12)
	v_lshlrev_b32_e32 v12, 16, v76
	v_and_b32_e32 v13, 0xffff0000, v76
	v_lshlrev_b32_e32 v14, 16, v77
	v_and_b32_e32 v15, 0xffff0000, v77
	s_waitcnt lgkmcnt(1)
	v_pk_fma_f32 v[4:5], v[4:5], 0.5, v[12:13] op_sel_hi:[1,0,1]
	v_lshlrev_b32_e32 v12, 16, v74
	v_and_b32_e32 v13, 0xffff0000, v74
	s_mov_b32 s0, 0x50000
	v_pk_fma_f32 v[6:7], v[6:7], 0.5, v[14:15] op_sel_hi:[1,0,1]
	v_lshlrev_b32_e32 v14, 16, v75
	v_and_b32_e32 v15, 0xffff0000, v75
	s_waitcnt lgkmcnt(0)
	v_pk_fma_f32 v[8:9], v[8:9], 0.5, v[12:13] op_sel_hi:[1,0,1]
	v_add_co_u32_e32 v12, vcc, s0, v2
	v_pk_fma_f32 v[10:11], v[10:11], 0.5, v[14:15] op_sel_hi:[1,0,1]
	s_nop 0
	v_addc_co_u32_e32 v13, vcc, 0, v3, vcc
	global_store_dwordx4 v[12:13], v[8:11], off nt
	global_store_dwordx4 v[12:13], v[4:7], off offset:16 nt
	ds_read_b128 v[4:7], v110
	ds_read_b128 v[8:11], v107
	s_waitcnt vmcnt(13)
	v_lshlrev_b32_e32 v12, 16, v72
	v_and_b32_e32 v13, 0xffff0000, v72
	v_lshlrev_b32_e32 v14, 16, v73
	v_and_b32_e32 v15, 0xffff0000, v73
	s_waitcnt lgkmcnt(1)
	v_pk_fma_f32 v[4:5], v[4:5], 0.5, v[12:13] op_sel_hi:[1,0,1]
	v_lshlrev_b32_e32 v12, 16, v70
	v_and_b32_e32 v13, 0xffff0000, v70
	s_mov_b32 s0, 0x60000
	v_pk_fma_f32 v[6:7], v[6:7], 0.5, v[14:15] op_sel_hi:[1,0,1]
	v_lshlrev_b32_e32 v14, 16, v71
	v_and_b32_e32 v15, 0xffff0000, v71
	s_waitcnt lgkmcnt(0)
	v_pk_fma_f32 v[8:9], v[8:9], 0.5, v[12:13] op_sel_hi:[1,0,1]
	v_add_co_u32_e32 v12, vcc, s0, v2
	v_pk_fma_f32 v[10:11], v[10:11], 0.5, v[14:15] op_sel_hi:[1,0,1]
	s_nop 0
	v_addc_co_u32_e32 v13, vcc, 0, v3, vcc
	global_store_dwordx4 v[12:13], v[8:11], off nt
	global_store_dwordx4 v[12:13], v[4:7], off offset:16 nt
	ds_read_b128 v[4:7], v111
	ds_read_b128 v[8:11], v109
	s_waitcnt vmcnt(14)
	v_lshlrev_b32_e32 v12, 16, v68
	v_and_b32_e32 v13, 0xffff0000, v68
	v_lshlrev_b32_e32 v14, 16, v69
	v_and_b32_e32 v15, 0xffff0000, v69
	s_waitcnt lgkmcnt(1)
	v_pk_fma_f32 v[4:5], v[4:5], 0.5, v[12:13] op_sel_hi:[1,0,1]
	v_pk_fma_f32 v[6:7], v[6:7], 0.5, v[14:15] op_sel_hi:[1,0,1]
	v_lshlrev_b32_e32 v12, 16, v66
	v_and_b32_e32 v13, 0xffff0000, v66
	v_lshlrev_b32_e32 v14, 16, v67
	v_and_b32_e32 v15, 0xffff0000, v67
	v_add_co_u32_e32 v2, vcc, 0x70000, v2
	s_waitcnt lgkmcnt(0)
	v_pk_fma_f32 v[8:9], v[8:9], 0.5, v[12:13] op_sel_hi:[1,0,1]
	v_pk_fma_f32 v[10:11], v[10:11], 0.5, v[14:15] op_sel_hi:[1,0,1]
	v_addc_co_u32_e32 v3, vcc, 0, v3, vcc
	global_store_dwordx4 v[2:3], v[8:11], off nt
	global_store_dwordx4 v[2:3], v[4:7], off offset:16 nt

.LBB0_2128:
	s_andn2_b64 vcc, exec, s[12:13]
	s_cbranch_vccnz .LBB0_2130
	v_lshl_add_u32 v132, s72, 8, v212
	v_lshl_or_b32 v130, s71, 8, v214
	v_ashrrev_i32_e32 v133, 31, v132
	v_ashrrev_i32_e32 v131, 31, v130
	v_lshlrev_b64 v[128:129], 10, v[132:133]
	v_lshl_add_u64 v[128:129], v[128:129], 0, v[130:131]
	v_lshl_add_u64 v[134:135], v[128:129], 1, s[88:89]
	global_load_dwordx2 v[136:137], v[134:135], off offset:288
	global_load_dwordx2 v[138:139], v[134:135], off offset:256
	global_load_dwordx2 v[140:141], v[134:135], off offset:32
	s_nop 0
	global_load_dwordx2 v[134:135], v[134:135], off
	v_or_b32_e32 v142, 16, v132
	v_ashrrev_i32_e32 v143, 31, v142
	v_lshlrev_b64 v[142:143], 10, v[142:143]
	v_lshl_add_u64 v[144:145], v[128:129], 2, s[84:85]
	v_lshl_add_u64 v[142:143], v[142:143], 0, v[130:131]
	v_lshl_add_u64 v[146:147], v[142:143], 1, s[88:89]
	s_waitcnt vmcnt(0)
	v_lshlrev_b32_e32 v148, 16, v136
	v_and_b32_e32 v149, 0xffff0000, v136
	v_lshlrev_b32_e32 v136, 16, v137
	v_lshlrev_b32_e32 v154, 16, v134
	v_and_b32_e32 v155, 0xffff0000, v134
	v_lshlrev_b32_e32 v134, 16, v135
	v_and_b32_e32 v135, 0xffff0000, v135
	v_and_b32_e32 v137, 0xffff0000, v137
	v_lshlrev_b32_e32 v150, 16, v138
	v_and_b32_e32 v151, 0xffff0000, v138
	v_lshlrev_b32_e32 v138, 16, v139
	v_and_b32_e32 v139, 0xffff0000, v139
	v_lshlrev_b32_e32 v152, 16, v140
	v_and_b32_e32 v153, 0xffff0000, v140
	v_lshlrev_b32_e32 v140, 16, v141
	v_and_b32_e32 v141, 0xffff0000, v141
	v_pk_fma_f32 v[118:119], v[118:119], 0.5, v[134:135] op_sel_hi:[1,0,1]
	v_pk_fma_f32 v[116:117], v[116:117], 0.5, v[154:155] op_sel_hi:[1,0,1]
	v_pk_fma_f32 v[114:115], v[114:115], 0.5, v[140:141] op_sel_hi:[1,0,1]
	v_pk_fma_f32 v[112:113], v[112:113], 0.5, v[152:153] op_sel_hi:[1,0,1]
	v_pk_fma_f32 v[126:127], v[126:127], 0.5, v[138:139] op_sel_hi:[1,0,1]
	v_pk_fma_f32 v[124:125], v[124:125], 0.5, v[150:151] op_sel_hi:[1,0,1]
	v_pk_fma_f32 v[122:123], v[122:123], 0.5, v[136:137] op_sel_hi:[1,0,1]
	v_pk_fma_f32 v[120:121], v[120:121], 0.5, v[148:149] op_sel_hi:[1,0,1]
	global_store_dwordx4 v[144:145], v[116:119], off nt
	global_store_dwordx4 v[144:145], v[112:115], off offset:64 nt
	global_store_dwordx4 v[144:145], v[124:127], off offset:512 nt
	global_store_dwordx4 v[144:145], v[120:123], off offset:576 nt
	global_load_dwordx2 v[112:113], v[146:147], off offset:288
	s_nop 0
	global_load_dwordx2 v[114:115], v[146:147], off offset:256
	global_load_dwordx2 v[116:117], v[146:147], off offset:32
	global_load_dwordx2 v[118:119], v[146:147], off
	v_or_b32_e32 v120, 32, v132
	v_ashrrev_i32_e32 v121, 31, v120
	v_lshlrev_b64 v[120:121], 10, v[120:121]
	v_lshl_add_u64 v[120:121], v[120:121], 0, v[130:131]
	v_lshl_add_u64 v[122:123], v[142:143], 2, s[84:85]
	v_lshl_add_u64 v[124:125], v[120:121], 1, s[88:89]
	s_waitcnt vmcnt(3)
	v_lshlrev_b32_e32 v126, 16, v112
	v_and_b32_e32 v127, 0xffff0000, v112
	v_lshlrev_b32_e32 v112, 16, v113
	s_waitcnt vmcnt(0)
	v_lshlrev_b32_e32 v138, 16, v118
	v_and_b32_e32 v139, 0xffff0000, v118
	v_lshlrev_b32_e32 v118, 16, v119
	v_and_b32_e32 v119, 0xffff0000, v119
	v_and_b32_e32 v113, 0xffff0000, v113
	v_lshlrev_b32_e32 v134, 16, v114
	v_and_b32_e32 v135, 0xffff0000, v114
	v_lshlrev_b32_e32 v114, 16, v115
	v_and_b32_e32 v115, 0xffff0000, v115
	v_lshlrev_b32_e32 v136, 16, v116
	v_and_b32_e32 v137, 0xffff0000, v116
	v_lshlrev_b32_e32 v116, 16, v117
	v_and_b32_e32 v117, 0xffff0000, v117
	v_pk_fma_f32 v[102:103], v[102:103], 0.5, v[118:119] op_sel_hi:[1,0,1]
	v_pk_fma_f32 v[100:101], v[100:101], 0.5, v[138:139] op_sel_hi:[1,0,1]
	v_pk_fma_f32 v[98:99], v[98:99], 0.5, v[116:117] op_sel_hi:[1,0,1]
	v_pk_fma_f32 v[96:97], v[96:97], 0.5, v[136:137] op_sel_hi:[1,0,1]
	v_pk_fma_f32 v[110:111], v[110:111], 0.5, v[114:115] op_sel_hi:[1,0,1]
	v_pk_fma_f32 v[108:109], v[108:109], 0.5, v[134:135] op_sel_hi:[1,0,1]
	v_pk_fma_f32 v[106:107], v[106:107], 0.5, v[112:113] op_sel_hi:[1,0,1]
	v_pk_fma_f32 v[104:105], v[104:105], 0.5, v[126:127] op_sel_hi:[1,0,1]
	global_store_dwordx4 v[122:123], v[100:103], off nt
	global_store_dwordx4 v[122:123], v[96:99], off offset:64 nt
	global_store_dwordx4 v[122:123], v[108:111], off offset:512 nt
	global_store_dwordx4 v[122:123], v[104:107], off offset:576 nt
	global_load_dwordx2 v[96:97], v[124:125], off offset:288
	s_nop 0
	global_load_dwordx2 v[98:99], v[124:125], off offset:256
	global_load_dwordx2 v[100:101], v[124:125], off offset:32
	global_load_dwordx2 v[102:103], v[124:125], off
	v_or_b32_e32 v104, 48, v132
	v_ashrrev_i32_e32 v105, 31, v104
	v_lshlrev_b64 v[104:105], 10, v[104:105]
	v_lshl_add_u64 v[104:105], v[104:105], 0, v[130:131]
	v_lshl_add_u64 v[106:107], v[120:121], 2, s[84:85]
	v_lshl_add_u64 v[108:109], v[104:105], 1, s[88:89]
	s_waitcnt vmcnt(3)
	v_lshlrev_b32_e32 v110, 16, v96
	v_and_b32_e32 v111, 0xffff0000, v96
	v_lshlrev_b32_e32 v96, 16, v97
	s_waitcnt vmcnt(0)
	v_lshlrev_b32_e32 v116, 16, v102
	v_and_b32_e32 v117, 0xffff0000, v102
	v_lshlrev_b32_e32 v102, 16, v103
	v_and_b32_e32 v103, 0xffff0000, v103
	v_and_b32_e32 v97, 0xffff0000, v97
	v_lshlrev_b32_e32 v112, 16, v98
	v_and_b32_e32 v113, 0xffff0000, v98
	v_lshlrev_b32_e32 v98, 16, v99
	v_and_b32_e32 v99, 0xffff0000, v99
	v_lshlrev_b32_e32 v114, 16, v100
	v_and_b32_e32 v115, 0xffff0000, v100
	v_lshlrev_b32_e32 v100, 16, v101
	v_and_b32_e32 v101, 0xffff0000, v101
	v_pk_fma_f32 v[86:87], v[86:87], 0.5, v[102:103] op_sel_hi:[1,0,1]
	v_pk_fma_f32 v[84:85], v[84:85], 0.5, v[116:117] op_sel_hi:[1,0,1]
	v_pk_fma_f32 v[82:83], v[82:83], 0.5, v[100:101] op_sel_hi:[1,0,1]
	v_pk_fma_f32 v[80:81], v[80:81], 0.5, v[114:115] op_sel_hi:[1,0,1]
	v_pk_fma_f32 v[94:95], v[94:95], 0.5, v[98:99] op_sel_hi:[1,0,1]
	v_pk_fma_f32 v[92:93], v[92:93], 0.5, v[112:113] op_sel_hi:[1,0,1]
	v_pk_fma_f32 v[90:91], v[90:91], 0.5, v[96:97] op_sel_hi:[1,0,1]
	v_pk_fma_f32 v[88:89], v[88:89], 0.5, v[110:111] op_sel_hi:[1,0,1]
	global_store_dwordx4 v[106:107], v[84:87], off nt
	global_store_dwordx4 v[106:107], v[80:83], off offset:64 nt
	global_store_dwordx4 v[106:107], v[92:95], off offset:512 nt
	global_store_dwordx4 v[106:107], v[88:91], off offset:576 nt
	global_load_dwordx2 v[80:81], v[108:109], off offset:288
	s_nop 0
	global_load_dwordx2 v[82:83], v[108:109], off offset:256
	global_load_dwordx2 v[84:85], v[108:109], off offset:32
	global_load_dwordx2 v[86:87], v[108:109], off
	v_lshl_add_u64 v[88:89], v[128:129], 0, s[20:21]
	v_lshl_add_u64 v[90:91], v[104:105], 2, s[84:85]
	v_lshl_add_u64 v[92:93], v[88:89], 1, s[88:89]
	s_waitcnt vmcnt(3)
	v_lshlrev_b32_e32 v94, 16, v80
	v_and_b32_e32 v95, 0xffff0000, v80
	v_lshlrev_b32_e32 v80, 16, v81
	s_waitcnt vmcnt(0)
	v_lshlrev_b32_e32 v100, 16, v86
	v_and_b32_e32 v101, 0xffff0000, v86
	v_lshlrev_b32_e32 v86, 16, v87
	v_and_b32_e32 v87, 0xffff0000, v87
	v_and_b32_e32 v81, 0xffff0000, v81
	v_lshlrev_b32_e32 v96, 16, v82
	v_and_b32_e32 v97, 0xffff0000, v82
	v_lshlrev_b32_e32 v82, 16, v83
	v_and_b32_e32 v83, 0xffff0000, v83
	v_lshlrev_b32_e32 v98, 16, v84
	v_and_b32_e32 v99, 0xffff0000, v84
	v_lshlrev_b32_e32 v84, 16, v85
	v_and_b32_e32 v85, 0xffff0000, v85
	v_pk_fma_f32 v[70:71], v[70:71], 0.5, v[86:87] op_sel_hi:[1,0,1]
	v_pk_fma_f32 v[68:69], v[68:69], 0.5, v[100:101] op_sel_hi:[1,0,1]
	v_pk_fma_f32 v[66:67], v[66:67], 0.5, v[84:85] op_sel_hi:[1,0,1]
	v_pk_fma_f32 v[64:65], v[64:65], 0.5, v[98:99] op_sel_hi:[1,0,1]
	v_pk_fma_f32 v[78:79], v[78:79], 0.5, v[82:83] op_sel_hi:[1,0,1]
	v_pk_fma_f32 v[76:77], v[76:77], 0.5, v[96:97] op_sel_hi:[1,0,1]
	v_pk_fma_f32 v[74:75], v[74:75], 0.5, v[80:81] op_sel_hi:[1,0,1]
	v_pk_fma_f32 v[72:73], v[72:73], 0.5, v[94:95] op_sel_hi:[1,0,1]
	global_store_dwordx4 v[90:91], v[68:71], off nt
	global_store_dwordx4 v[90:91], v[64:67], off offset:64 nt
	global_store_dwordx4 v[90:91], v[76:79], off offset:512 nt
	global_store_dwordx4 v[90:91], v[72:75], off offset:576 nt
	global_load_dwordx2 v[64:65], v[92:93], off offset:288
	s_nop 0
	global_load_dwordx2 v[66:67], v[92:93], off offset:256
	global_load_dwordx2 v[68:69], v[92:93], off offset:32
	global_load_dwordx2 v[70:71], v[92:93], off
	v_lshl_add_u64 v[72:73], v[128:129], 0, s[22:23]
	v_lshl_add_u64 v[74:75], v[88:89], 2, s[84:85]
	v_lshl_add_u64 v[76:77], v[72:73], 1, s[88:89]
	s_waitcnt vmcnt(3)
	v_lshlrev_b32_e32 v78, 16, v64
	v_and_b32_e32 v79, 0xffff0000, v64
	v_lshlrev_b32_e32 v64, 16, v65
	s_waitcnt vmcnt(0)
	v_lshlrev_b32_e32 v84, 16, v70
	v_and_b32_e32 v85, 0xffff0000, v70
	v_lshlrev_b32_e32 v70, 16, v71
	v_and_b32_e32 v71, 0xffff0000, v71
	v_and_b32_e32 v65, 0xffff0000, v65
	v_lshlrev_b32_e32 v80, 16, v66
	v_and_b32_e32 v81, 0xffff0000, v66
	v_lshlrev_b32_e32 v66, 16, v67
	v_and_b32_e32 v67, 0xffff0000, v67
	v_lshlrev_b32_e32 v82, 16, v68
	v_and_b32_e32 v83, 0xffff0000, v68
	v_lshlrev_b32_e32 v68, 16, v69
	v_and_b32_e32 v69, 0xffff0000, v69
	v_pk_fma_f32 v[50:51], v[50:51], 0.5, v[70:71] op_sel_hi:[1,0,1]
	v_pk_fma_f32 v[48:49], v[48:49], 0.5, v[84:85] op_sel_hi:[1,0,1]
	v_pk_fma_f32 v[54:55], v[54:55], 0.5, v[68:69] op_sel_hi:[1,0,1]
	v_pk_fma_f32 v[52:53], v[52:53], 0.5, v[82:83] op_sel_hi:[1,0,1]
	v_pk_fma_f32 v[58:59], v[58:59], 0.5, v[66:67] op_sel_hi:[1,0,1]
	v_pk_fma_f32 v[56:57], v[56:57], 0.5, v[80:81] op_sel_hi:[1,0,1]
	v_pk_fma_f32 v[62:63], v[62:63], 0.5, v[64:65] op_sel_hi:[1,0,1]
	v_pk_fma_f32 v[60:61], v[60:61], 0.5, v[78:79] op_sel_hi:[1,0,1]
	global_store_dwordx4 v[74:75], v[48:51], off nt
	global_store_dwordx4 v[74:75], v[52:55], off offset:64 nt
	global_store_dwordx4 v[74:75], v[56:59], off offset:512 nt
	global_store_dwordx4 v[74:75], v[60:63], off offset:576 nt
	global_load_dwordx2 v[48:49], v[76:77], off offset:288
	s_nop 0
	global_load_dwordx2 v[50:51], v[76:77], off offset:256
	global_load_dwordx2 v[52:53], v[76:77], off offset:32
	global_load_dwordx2 v[54:55], v[76:77], off
	v_lshl_add_u64 v[56:57], v[128:129], 0, s[24:25]
	v_lshl_add_u64 v[58:59], v[72:73], 2, s[84:85]
	v_lshl_add_u64 v[60:61], v[56:57], 1, s[88:89]
	s_waitcnt vmcnt(3)
	v_lshlrev_b32_e32 v62, 16, v48
	v_and_b32_e32 v63, 0xffff0000, v48
	v_lshlrev_b32_e32 v48, 16, v49
	s_waitcnt vmcnt(0)
	v_lshlrev_b32_e32 v68, 16, v54
	v_and_b32_e32 v69, 0xffff0000, v54
	v_lshlrev_b32_e32 v54, 16, v55
	v_and_b32_e32 v55, 0xffff0000, v55
	v_and_b32_e32 v49, 0xffff0000, v49
	v_lshlrev_b32_e32 v64, 16, v50
	v_and_b32_e32 v65, 0xffff0000, v50
	v_lshlrev_b32_e32 v50, 16, v51
	v_and_b32_e32 v51, 0xffff0000, v51
	v_lshlrev_b32_e32 v66, 16, v52
	v_and_b32_e32 v67, 0xffff0000, v52
	v_lshlrev_b32_e32 v52, 16, v53
	v_and_b32_e32 v53, 0xffff0000, v53
	v_pk_fma_f32 v[34:35], v[34:35], 0.5, v[54:55] op_sel_hi:[1,0,1]
	v_pk_fma_f32 v[32:33], v[32:33], 0.5, v[68:69] op_sel_hi:[1,0,1]
	v_pk_fma_f32 v[38:39], v[38:39], 0.5, v[52:53] op_sel_hi:[1,0,1]
	v_pk_fma_f32 v[36:37], v[36:37], 0.5, v[66:67] op_sel_hi:[1,0,1]
	v_pk_fma_f32 v[42:43], v[42:43], 0.5, v[50:51] op_sel_hi:[1,0,1]
	v_pk_fma_f32 v[40:41], v[40:41], 0.5, v[64:65] op_sel_hi:[1,0,1]
	v_pk_fma_f32 v[46:47], v[46:47], 0.5, v[48:49] op_sel_hi:[1,0,1]
	v_pk_fma_f32 v[44:45], v[44:45], 0.5, v[62:63] op_sel_hi:[1,0,1]
	global_store_dwordx4 v[58:59], v[32:35], off nt
	global_store_dwordx4 v[58:59], v[36:39], off offset:64 nt
	global_store_dwordx4 v[58:59], v[40:43], off offset:512 nt
	global_store_dwordx4 v[58:59], v[44:47], off offset:576 nt
	global_load_dwordx2 v[32:33], v[60:61], off offset:288
	s_nop 0
	global_load_dwordx2 v[34:35], v[60:61], off offset:256
	global_load_dwordx2 v[36:37], v[60:61], off offset:32
	global_load_dwordx2 v[38:39], v[60:61], off
	v_lshl_add_u64 v[40:41], v[128:129], 0, s[26:27]
	v_lshl_add_u64 v[42:43], v[56:57], 2, s[84:85]
	v_lshl_add_u64 v[44:45], v[40:41], 1, s[88:89]
	s_waitcnt vmcnt(3)
	v_lshlrev_b32_e32 v46, 16, v32
	v_and_b32_e32 v47, 0xffff0000, v32
	v_lshlrev_b32_e32 v32, 16, v33
	s_waitcnt vmcnt(0)
	v_lshlrev_b32_e32 v52, 16, v38
	v_and_b32_e32 v53, 0xffff0000, v38
	v_lshlrev_b32_e32 v38, 16, v39
	v_and_b32_e32 v39, 0xffff0000, v39
	v_and_b32_e32 v33, 0xffff0000, v33
	v_lshlrev_b32_e32 v48, 16, v34
	v_and_b32_e32 v49, 0xffff0000, v34
	v_lshlrev_b32_e32 v34, 16, v35
	v_and_b32_e32 v35, 0xffff0000, v35
	v_lshlrev_b32_e32 v50, 16, v36
	v_and_b32_e32 v51, 0xffff0000, v36
	v_lshlrev_b32_e32 v36, 16, v37
	v_and_b32_e32 v37, 0xffff0000, v37
	v_pk_fma_f32 v[18:19], v[18:19], 0.5, v[38:39] op_sel_hi:[1,0,1]
	v_pk_fma_f32 v[16:17], v[16:17], 0.5, v[52:53] op_sel_hi:[1,0,1]
	v_pk_fma_f32 v[22:23], v[22:23], 0.5, v[36:37] op_sel_hi:[1,0,1]
	v_pk_fma_f32 v[20:21], v[20:21], 0.5, v[50:51] op_sel_hi:[1,0,1]
	v_pk_fma_f32 v[26:27], v[26:27], 0.5, v[34:35] op_sel_hi:[1,0,1]
	v_pk_fma_f32 v[24:25], v[24:25], 0.5, v[48:49] op_sel_hi:[1,0,1]
	v_pk_fma_f32 v[30:31], v[30:31], 0.5, v[32:33] op_sel_hi:[1,0,1]
	v_pk_fma_f32 v[28:29], v[28:29], 0.5, v[46:47] op_sel_hi:[1,0,1]
	global_store_dwordx4 v[42:43], v[16:19], off nt
	global_store_dwordx4 v[42:43], v[20:23], off offset:64 nt
	global_store_dwordx4 v[42:43], v[24:27], off offset:512 nt
	global_store_dwordx4 v[42:43], v[28:31], off offset:576 nt
	global_load_dwordx2 v[16:17], v[44:45], off offset:288
	s_nop 0
	global_load_dwordx2 v[18:19], v[44:45], off offset:256
	global_load_dwordx2 v[20:21], v[44:45], off offset:32
	global_load_dwordx2 v[22:23], v[44:45], off
	v_lshl_add_u64 v[24:25], v[40:41], 2, s[84:85]
	s_waitcnt vmcnt(3)
	v_lshlrev_b32_e32 v26, 16, v16
	v_and_b32_e32 v27, 0xffff0000, v16
	v_lshlrev_b32_e32 v16, 16, v17
	s_waitcnt vmcnt(0)
	v_lshlrev_b32_e32 v32, 16, v22
	v_and_b32_e32 v33, 0xffff0000, v22
	v_lshlrev_b32_e32 v22, 16, v23
	v_and_b32_e32 v23, 0xffff0000, v23
	v_and_b32_e32 v17, 0xffff0000, v17
	v_lshlrev_b32_e32 v28, 16, v18
	v_and_b32_e32 v29, 0xffff0000, v18
	v_lshlrev_b32_e32 v18, 16, v19
	v_and_b32_e32 v19, 0xffff0000, v19
	v_lshlrev_b32_e32 v30, 16, v20
	v_and_b32_e32 v31, 0xffff0000, v20
	v_lshlrev_b32_e32 v20, 16, v21
	v_and_b32_e32 v21, 0xffff0000, v21
	v_pk_fma_f32 v[14:15], v[14:15], 0.5, v[22:23] op_sel_hi:[1,0,1]
	v_pk_fma_f32 v[12:13], v[12:13], 0.5, v[32:33] op_sel_hi:[1,0,1]
	v_pk_fma_f32 v[6:7], v[6:7], 0.5, v[20:21] op_sel_hi:[1,0,1]
	v_pk_fma_f32 v[4:5], v[4:5], 0.5, v[30:31] op_sel_hi:[1,0,1]
	v_pk_fma_f32 v[10:11], v[10:11], 0.5, v[18:19] op_sel_hi:[1,0,1]
	v_pk_fma_f32 v[8:9], v[8:9], 0.5, v[28:29] op_sel_hi:[1,0,1]
	v_pk_fma_f32 v[2:3], v[2:3], 0.5, v[16:17] op_sel_hi:[1,0,1]
	v_pk_fma_f32 v[0:1], v[0:1], 0.5, v[26:27] op_sel_hi:[1,0,1]
	global_store_dwordx4 v[24:25], v[12:15], off nt
	global_store_dwordx4 v[24:25], v[4:7], off offset:64 nt
	global_store_dwordx4 v[24:25], v[8:11], off offset:512 nt
	global_store_dwordx4 v[24:25], v[0:3], off offset:576 nt
